# GEMM phase prologues: both cold-start DMA batches issued before the first wait (8 phases)
# speedup vs baseline: 1.0097x; 1.0097x over previous
.LBB0_179:
	v_writelane_b32 v255, s90, 12
	s_lshl_b64 s[8:9], s[90:91], 2
	v_readlane_b32 s16, v253, 21
	v_readlane_b32 s17, v253, 22
	s_add_u32 s6, s16, s8
	v_readlane_b32 s22, v253, 27
	s_addc_u32 s7, s17, s9
	v_readlane_b32 s78, v254, 48
	v_readlane_b32 s23, v253, 28
	s_add_u32 s8, s22, s8
	v_mov_b32_e32 v173, v161
	v_readlane_b32 s79, v254, 49
	s_addc_u32 s9, s23, s9
	s_and_b32 s15, s4, 3
	s_add_i32 m0, s88, 0x18000
	v_lshl_add_u64 v[0:1], v[0:1], 0, s[38:39]
	v_lshl_add_u64 v[12:13], s[78:79], 0, v[172:173]
	v_mov_b32_e32 v169, v161
	s_lshl_b32 s10, s3, 13
	s_lshl_b32 s11, s15, 12
	global_load_lds_dwordx4 v[0:1], off
	v_lshl_add_u64 v[0:1], v[2:3], 0, s[38:39]
	s_add_i32 m0, s88, 0x1a000
	s_add_i32 s35, s88, 0x8000
	s_add_i32 s14, s88, 0xa000
	v_lshl_add_u64 v[14:15], s[78:79], 0, v[168:169]
	global_load_lds_dwordx4 v[0:1], off
	v_lshl_add_u64 v[0:1], v[12:13], 0, s[38:39]
	s_mov_b32 m0, s35
	s_add_u32 s4, s50, 0x40080
	global_load_lds_dwordx4 v[0:1], off
	v_lshl_add_u64 v[0:1], v[14:15], 0, s[38:39]
	s_mov_b32 m0, s14
	s_addc_u32 s5, s51, 0
	global_load_lds_dwordx4 v[0:1], off
	s_add_i32 m0, s88, 0x1c000
	v_lshl_add_u64 v[0:1], s[4:5], 0, v[170:171]
	global_load_lds_dwordx4 v[0:1], off
	v_lshl_add_u64 v[0:1], s[4:5], 0, v[166:167]
	s_add_i32 m0, s88, 0x1e000
	v_bfe_u32 v175, v6, 4, 2
	global_load_lds_dwordx4 v[0:1], off
	s_waitcnt vmcnt(8)
	s_barrier
	v_and_b32_e32 v1, 15, v6
	v_lshlrev_b32_e32 v2, 4, v175
	v_lshl_or_b32 v207, s3, 6, v1
	v_lshl_or_b32 v1, v1, 6, v2
	v_lshlrev_b32_e32 v2, 2, v6
	v_and_b32_e32 v2, 32, v2
	v_bitop3_b32 v3, v1, s10, v2 bitop3:0xde
	v_bitop3_b32 v208, v1, s11, v2 bitop3:0xde
	v_lshlrev_b32_e32 v1, 14, v9
	v_and_b32_e32 v1, 0xffff8000, v1
	v_lshl_add_u32 v1, v8, 11, v1
	v_and_b32_e32 v2, 1, v9
	s_cmpk_lt_u32 s2, 0x100
	v_lshl_or_b32 v1, v2, 6, v1
	s_cselect_b64 s[10:11], -1, 0
	s_add_u32 s2, s8, 0x100
	v_lshl_add_u32 v176, v10, 1, v1
	v_lshlrev_b32_e32 v1, 14, v4
	v_writelane_b32 v255, s91, 13
	s_addc_u32 s3, s9, 0
	v_and_b32_e32 v1, 0xffff8000, v1
	v_lshlrev_b32_e32 v0, 3, v175
	s_waitcnt vmcnt(6)
	v_writelane_b32 v255, s2, 14
	v_lshl_add_u32 v1, v5, 11, v1
	v_and_b32_e32 v2, 1, v4
	v_lshl_or_b32 v174, s15, 6, v0
	v_writelane_b32 v255, s3, 15
	s_add_u32 s16, s6, 0x100
	v_lshl_or_b32 v1, v2, 6, v1
	v_readlane_b32 s2, v254, 46
	v_readlane_b32 s18, v253, 23
	v_readlane_b32 s20, v253, 25
	v_or_b32_e32 v209, 16, v207
	v_or_b32_e32 v210, 32, v207
	v_or_b32_e32 v211, 48, v207
	s_addc_u32 s17, s7, 0
	v_mov_b32_e32 v177, v161
	v_lshl_add_u32 v178, v7, 1, v1
	v_mov_b32_e32 v179, v161
	s_mov_b32 s15, 0
	v_add_u32_e32 v212, 0, v3
	v_lshlrev_b32_e32 v213, 2, v174
	v_lshlrev_b32_e32 v214, 2, v0
	v_readlane_b32 s96, v254, 16
	s_mov_b32 s56, s2
	s_mov_b64 s[4:5], s[78:79]
	v_readlane_b32 s19, v253, 24
	v_readlane_b32 s21, v253, 26
	v_readlane_b32 s24, v253, 29
	v_readlane_b32 s25, v253, 30
	v_readlane_b32 s26, v253, 31
	v_readlane_b32 s27, v253, 32
	v_readlane_b32 s28, v253, 33
	v_readlane_b32 s29, v253, 34
	v_readlane_b32 s30, v253, 35
	v_readlane_b32 s31, v253, 36
	s_barrier
	v_readlane_b32 s3, v254, 47
	s_branch .LBB0_182

.LBB0_469:
	s_add_u32 s35, s65, 0x6400
	s_addc_u32 s84, s94, 0
	v_lshrrev_b32_e32 v16, 1, v10
	s_add_u32 s8, s0, 0x1000
	v_and_b32_e32 v16, 24, v16
	v_readlane_b32 s20, v254, 21
	s_addc_u32 s9, s1, 0
	v_and_b32_e32 v11, 15, v10
	v_lshlrev_b32_e32 v17, 1, v16
	v_lshlrev_b32_e32 v10, 2, v10
	s_lshl_b32 s3, s3, 5
	v_mov_b32_e32 v133, v161
	v_readlane_b32 s21, v254, 22
	v_lshl_or_b32 v166, s4, 6, v11
	v_lshl_or_b32 v11, v11, 6, v17
	s_lshl_b32 s4, s4, 13
	v_and_b32_e32 v10, 32, v10
	s_and_b32 s3, s3, 0x60
	s_add_i32 m0, s29, 0x18000
	v_lshl_add_u64 v[0:1], v[0:1], 0, s[38:39]
	v_lshl_add_u64 v[12:13], s[20:21], 0, v[132:133]
	v_mov_b32_e32 v131, v161
	v_bitop3_b32 v17, v11, s4, v10 bitop3:0xde
	s_lshl_b32 s4, s3, 7
	global_load_lds_dwordx4 v[0:1], off
	v_lshl_add_u64 v[0:1], v[2:3], 0, s[38:39]
	s_add_i32 m0, s29, 0x1a000
	s_add_i32 s85, s29, 0x8000
	s_add_i32 s86, s29, 0xa000
	v_lshl_add_u64 v[14:15], s[20:21], 0, v[130:131]
	v_bitop3_b32 v167, v11, s4, v10 bitop3:0xde
	global_load_lds_dwordx4 v[0:1], off
	v_lshl_add_u64 v[0:1], v[12:13], 0, s[38:39]
	s_mov_b32 m0, s85
	s_add_u32 s4, s22, 0x40080
	global_load_lds_dwordx4 v[0:1], off
	v_lshl_add_u64 v[0:1], v[14:15], 0, s[38:39]
	s_mov_b32 m0, s86
	s_addc_u32 s5, s23, 0
	global_load_lds_dwordx4 v[0:1], off
	s_add_i32 m0, s29, 0x1c000
	v_lshl_add_u64 v[0:1], s[4:5], 0, v[160:161]
	global_load_lds_dwordx4 v[0:1], off
	v_lshl_add_u64 v[0:1], s[4:5], 0, v[128:129]
	s_add_i32 m0, s29, 0x1e000
	s_cmpk_lt_u32 s2, 0x100
	global_load_lds_dwordx4 v[0:1], off
	s_waitcnt vmcnt(8)
	s_barrier
	v_lshlrev_b32_e32 v0, 14, v8
	v_and_b32_e32 v0, 0xffff8000, v0
	v_lshl_add_u32 v0, v7, 11, v0
	v_and_b32_e32 v1, 1, v8
	v_lshl_or_b32 v0, v1, 6, v0
	v_lshl_add_u32 v134, v9, 1, v0
	v_lshlrev_b32_e32 v0, 14, v4
	v_and_b32_e32 v0, 0xffff8000, v0
	s_waitcnt vmcnt(6)
	v_lshl_add_u32 v0, v5, 11, v0
	v_and_b32_e32 v1, 1, v4
	v_lshl_or_b32 v0, v1, 6, v0
	v_readlane_b32 s4, v254, 58
	s_cselect_b64 s[10:11], -1, 0
	v_or_b32_e32 v168, s3, v16
	v_mov_b32_e32 v135, v161
	v_lshl_add_u32 v136, v6, 1, v0
	v_mov_b32_e32 v137, v161
	s_mov_b32 s88, 0
	v_add_u32_e32 v169, 0, v17
	v_readlane_b32 s3, v254, 18
	s_mov_b32 s2, s4
	s_barrier
	v_readlane_b32 s5, v254, 59
	s_branch .LBB0_472

.LBB0_489:
	v_lshrrev_b32_e32 v10, 1, v0
	v_and_b32_e32 v10, 24, v10
	v_and_b32_e32 v1, 15, v0
	v_lshlrev_b32_e32 v11, 1, v10
	v_lshlrev_b32_e32 v0, 2, v0
	s_lshl_b32 s5, s5, 5
	v_lshl_or_b32 v138, s8, 6, v1
	v_lshl_or_b32 v1, v1, 6, v11
	s_lshl_b32 s8, s8, 13
	v_and_b32_e32 v0, 32, v0
	s_and_b32 s5, s5, 0x60
	v_lshl_add_u64 v[2:3], s[20:21], 0, v[160:161]
	v_mov_b32_e32 v129, v161
	v_readlane_b32 s26, v254, 27
	v_bitop3_b32 v11, v1, s8, v0 bitop3:0xde
	s_lshl_b32 s8, s5, 7
	v_lshl_add_u64 v[4:5], s[20:21], 0, v[128:129]
	v_mov_b32_e32 v133, v161
	v_readlane_b32 s27, v254, 28
	v_bitop3_b32 v139, v1, s8, v0 bitop3:0xde
	s_add_i32 m0, s29, 0x18000
	v_lshl_add_u64 v[0:1], v[2:3], 0, s[38:39]
	v_lshl_add_u64 v[6:7], s[26:27], 0, v[132:133]
	v_mov_b32_e32 v131, v161
	global_load_lds_dwordx4 v[0:1], off
	v_lshl_add_u64 v[0:1], v[4:5], 0, s[38:39]
	s_add_i32 m0, s29, 0x1a000
	s_add_i32 s35, s29, 0x8000
	s_add_i32 s84, s29, 0xa000
	v_lshl_add_u64 v[8:9], s[26:27], 0, v[130:131]
	global_load_lds_dwordx4 v[0:1], off
	v_lshl_add_u64 v[0:1], v[6:7], 0, s[38:39]
	s_mov_b32 m0, s35
	s_add_u32 s8, s20, 0x10080
	global_load_lds_dwordx4 v[0:1], off
	v_lshl_add_u64 v[0:1], v[8:9], 0, s[38:39]
	s_mov_b32 m0, s84
	s_addc_u32 s9, s21, 0
	global_load_lds_dwordx4 v[0:1], off
	s_add_i32 m0, s29, 0x1c000
	v_lshl_add_u64 v[0:1], s[8:9], 0, v[160:161]
	global_load_lds_dwordx4 v[0:1], off
	v_lshl_add_u64 v[0:1], s[8:9], 0, v[128:129]
	s_add_i32 m0, s29, 0x1e000
	s_cmpk_lt_u32 s4, 0x100
	global_load_lds_dwordx4 v[0:1], off
	s_waitcnt vmcnt(8)
	s_barrier
	s_waitcnt vmcnt(6)
	v_or_b32_e32 v140, s5, v10
	v_readlane_b32 s10, v255, 2
	v_readlane_b32 s4, v254, 58
	s_cselect_b64 s[8:9], -1, 0
	v_add_u32_e32 v141, 0, v11
	v_readlane_b32 s11, v255, 3
	v_readlane_b32 s56, v254, 18
	s_mov_b32 s85, s4
	s_barrier
	v_readlane_b32 s5, v254, 59
	s_branch .LBB0_492

.LBB0_507:
	v_lshrrev_b32_e32 v16, 1, v10
	v_and_b32_e32 v16, 24, v16
	v_and_b32_e32 v11, 15, v10
	v_lshlrev_b32_e32 v17, 1, v16
	v_lshlrev_b32_e32 v10, 2, v10
	s_lshl_b32 s3, s3, 5
	v_lshl_or_b32 v166, s4, 6, v11
	v_lshl_or_b32 v11, v11, 6, v17
	s_lshl_b32 s4, s4, 13
	v_and_b32_e32 v10, 32, v10
	s_and_b32 s3, s3, 0x60
	v_bitop3_b32 v17, v11, s4, v10 bitop3:0xde
	s_lshl_b32 s4, s3, 7
	v_readlane_b32 s18, v254, 21
	s_add_u32 s31, s65, 0x5400
	v_mov_b32_e32 v133, v161
	v_readlane_b32 s19, v254, 22
	s_addc_u32 s34, s94, 0
	s_add_i32 m0, s27, 0x18000
	v_lshl_add_u64 v[0:1], v[0:1], 0, s[38:39]
	v_lshl_add_u64 v[12:13], s[18:19], 0, v[132:133]
	v_mov_b32_e32 v131, v161
	global_load_lds_dwordx4 v[0:1], off
	v_lshl_add_u64 v[0:1], v[2:3], 0, s[38:39]
	s_add_i32 m0, s27, 0x1a000
	s_add_i32 s35, s27, 0x8000
	s_add_i32 s65, s27, 0xa000
	v_lshl_add_u64 v[14:15], s[18:19], 0, v[130:131]
	v_bitop3_b32 v167, v11, s4, v10 bitop3:0xde
	global_load_lds_dwordx4 v[0:1], off
	v_lshl_add_u64 v[0:1], v[12:13], 0, s[38:39]
	s_mov_b32 m0, s35
	s_add_u32 s4, s20, 0x40080
	global_load_lds_dwordx4 v[0:1], off
	v_lshl_add_u64 v[0:1], v[14:15], 0, s[38:39]
	s_mov_b32 m0, s65
	s_addc_u32 s5, s21, 0
	global_load_lds_dwordx4 v[0:1], off
	s_add_i32 m0, s27, 0x1c000
	v_lshl_add_u64 v[0:1], s[4:5], 0, v[160:161]
	global_load_lds_dwordx4 v[0:1], off
	v_lshl_add_u64 v[0:1], s[4:5], 0, v[128:129]
	s_add_i32 m0, s27, 0x1e000
	s_cmpk_lt_u32 s2, 0x100
	global_load_lds_dwordx4 v[0:1], off
	s_waitcnt vmcnt(8)
	s_barrier
	v_lshlrev_b32_e32 v0, 14, v8
	v_and_b32_e32 v0, 0xffff8000, v0
	v_lshl_add_u32 v0, v7, 11, v0
	v_and_b32_e32 v1, 1, v8
	v_lshl_or_b32 v0, v1, 6, v0
	v_lshl_add_u32 v134, v9, 1, v0
	v_lshlrev_b32_e32 v0, 14, v4
	v_and_b32_e32 v0, 0xffff8000, v0
	s_waitcnt vmcnt(6)
	v_lshl_add_u32 v0, v5, 11, v0
	v_and_b32_e32 v1, 1, v4
	v_lshl_or_b32 v0, v1, 6, v0
	v_readlane_b32 s4, v254, 58
	s_cselect_b64 s[8:9], -1, 0
	v_or_b32_e32 v168, s3, v16
	v_mov_b32_e32 v135, v161
	v_lshl_add_u32 v136, v6, 1, v0
	v_mov_b32_e32 v137, v161
	s_mov_b32 s84, 0
	v_add_u32_e32 v169, 0, v17
	v_readlane_b32 s3, v254, 18
	s_mov_b32 s2, s4
	s_barrier
	v_readlane_b32 s5, v254, 59
	s_branch .LBB0_510

.LBB0_527:
	v_lshrrev_b32_e32 v16, 1, v6
	v_and_b32_e32 v16, 24, v16
	v_and_b32_e32 v7, 15, v6
	v_lshlrev_b32_e32 v17, 1, v16
	v_lshlrev_b32_e32 v6, 2, v6
	s_lshl_b32 s3, s3, 5
	v_lshl_or_b32 v144, s4, 6, v7
	v_lshl_or_b32 v7, v7, 6, v17
	s_lshl_b32 s4, s4, 13
	v_and_b32_e32 v6, 32, v6
	s_and_b32 s3, s3, 0x60
	v_lshl_add_u64 v[8:9], s[18:19], 0, v[160:161]
	v_mov_b32_e32 v129, v161
	v_readlane_b32 s16, v254, 31
	v_bitop3_b32 v17, v7, s4, v6 bitop3:0xde
	s_lshl_b32 s4, s3, 7
	v_lshl_add_u64 v[10:11], s[18:19], 0, v[128:129]
	v_mov_b32_e32 v133, v161
	v_readlane_b32 s17, v254, 32
	v_bitop3_b32 v145, v7, s4, v6 bitop3:0xde
	s_add_i32 m0, s25, 0x18000
	v_lshl_add_u64 v[6:7], v[8:9], 0, s[38:39]
	v_lshl_add_u64 v[12:13], s[16:17], 0, v[132:133]
	v_mov_b32_e32 v131, v161
	global_load_lds_dwordx4 v[6:7], off
	v_lshl_add_u64 v[6:7], v[10:11], 0, s[38:39]
	s_add_i32 m0, s25, 0x1a000
	s_add_i32 s29, s25, 0x8000
	s_add_i32 s30, s25, 0xa000
	v_lshl_add_u64 v[14:15], s[16:17], 0, v[130:131]
	global_load_lds_dwordx4 v[6:7], off
	v_lshl_add_u64 v[6:7], v[12:13], 0, s[38:39]
	s_mov_b32 m0, s29
	s_add_u32 s4, s18, 0x40080
	global_load_lds_dwordx4 v[6:7], off
	v_lshl_add_u64 v[6:7], v[14:15], 0, s[38:39]
	s_mov_b32 m0, s30
	s_addc_u32 s5, s19, 0
	global_load_lds_dwordx4 v[6:7], off
	s_add_i32 m0, s25, 0x1c000
	v_lshl_add_u64 v[6:7], s[4:5], 0, v[160:161]
	global_load_lds_dwordx4 v[6:7], off
	v_lshl_add_u64 v[6:7], s[4:5], 0, v[128:129]
	s_add_i32 m0, s25, 0x1e000
	s_cmpk_lt_u32 s2, 0x100
	global_load_lds_dwordx4 v[6:7], off
	s_waitcnt vmcnt(8)
	s_barrier
	v_lshlrev_b32_e32 v6, 14, v4
	v_and_b32_e32 v6, 0xffff8000, v6
	v_lshl_add_u32 v3, v3, 11, v6
	v_and_b32_e32 v4, 1, v4
	v_lshl_or_b32 v3, v4, 6, v3
	v_lshl_add_u32 v134, v5, 1, v3
	v_lshlrev_b32_e32 v3, 14, v0
	v_and_b32_e32 v3, 0xffff8000, v3
	s_waitcnt vmcnt(6)
	v_lshl_add_u32 v1, v1, 11, v3
	v_and_b32_e32 v0, 1, v0
	v_lshl_or_b32 v0, v0, 6, v1
	v_readlane_b32 s4, v254, 58
	s_cselect_b64 s[6:7], -1, 0
	v_or_b32_e32 v146, s3, v16
	v_mov_b32_e32 v135, v161
	v_lshl_add_u32 v136, v2, 1, v0
	v_mov_b32_e32 v137, v161
	s_mov_b32 s31, 0
	v_add_u32_e32 v147, 0, v17
	v_readlane_b32 s2, v254, 18
	s_mov_b32 s3, s4
	s_barrier
	v_readlane_b32 s5, v254, 59
	s_branch .LBB0_530

.LBB0_593:
	v_readlane_b32 s6, v255, 6
	v_readlane_b32 s7, v255, 7
	v_readlane_b32 s8, v253, 5
	s_and_b64 s[6:7], s[6:7], exec
	v_readlane_b32 s9, v253, 6
	v_readlane_b32 s10, v253, 7
	v_readlane_b32 s11, v253, 8
	s_cselect_b32 s11, s73, s9
	s_cselect_b32 s10, s72, s8
	s_add_u32 s89, s91, 0x2000
	s_addc_u32 s95, s94, 0
	s_lshl_b32 s86, s90, 10
	v_readlane_b32 s14, v253, 11
	v_readlane_b32 s20, v253, 17
	s_lshl_b64 s[6:7], s[86:87], 2
	v_readlane_b32 s15, v253, 12
	v_readlane_b32 s21, v253, 18
	s_add_u32 s14, s20, s6
	s_addc_u32 s15, s21, s7
	s_add_u32 s86, s91, 0x4000
	s_addc_u32 s2, s94, 0
	v_bfe_u32 v11, v10, 4, 2
	s_lshl_b32 s3, s3, 5
	v_readlane_b32 s24, v254, 52
	v_and_b32_e32 v16, 15, v10
	v_lshlrev_b32_e32 v17, 4, v11
	v_lshlrev_b32_e32 v10, 2, v10
	s_and_b32 s8, s3, 0x60
	v_mov_b32_e32 v149, v161
	v_readlane_b32 s25, v254, 53
	v_lshl_or_b32 v186, s5, 6, v16
	v_lshl_or_b32 v16, v16, 6, v17
	v_and_b32_e32 v10, 32, v10
	s_lshl_b32 s3, s8, 7
	s_add_i32 m0, s35, 0x18000
	v_lshl_add_u64 v[0:1], v[0:1], 0, s[38:39]
	v_lshl_add_u64 v[12:13], s[24:25], 0, v[148:149]
	v_mov_b32_e32 v147, v161
	s_lshl_b32 s5, s5, 13
	v_bitop3_b32 v187, v16, s3, v10 bitop3:0xde
	global_load_lds_dwordx4 v[0:1], off
	v_lshl_add_u64 v[0:1], v[2:3], 0, s[38:39]
	s_add_i32 m0, s35, 0x1a000
	s_add_i32 s3, s35, 0x8000
	s_add_i32 s65, s35, 0xa000
	v_lshl_add_u64 v[14:15], s[24:25], 0, v[146:147]
	global_load_lds_dwordx4 v[0:1], off
	v_lshl_add_u64 v[0:1], v[12:13], 0, s[38:39]
	s_mov_b32 m0, s3
	s_add_u32 s6, s26, 0x40080
	global_load_lds_dwordx4 v[0:1], off
	v_lshl_add_u64 v[0:1], v[14:15], 0, s[38:39]
	s_mov_b32 m0, s65
	s_addc_u32 s7, s27, 0
	global_load_lds_dwordx4 v[0:1], off
	s_add_i32 m0, s35, 0x1c000
	v_lshl_add_u64 v[0:1], s[6:7], 0, v[160:161]
	global_load_lds_dwordx4 v[0:1], off
	v_lshl_add_u64 v[0:1], s[6:7], 0, v[144:145]
	s_add_i32 m0, s35, 0x1e000
	v_readlane_b32 s16, v253, 13
	global_load_lds_dwordx4 v[0:1], off
	s_waitcnt vmcnt(8)
	s_barrier
	v_lshlrev_b32_e32 v0, 14, v8
	v_and_b32_e32 v0, 0xffff8000, v0
	v_lshl_add_u32 v0, v7, 11, v0
	v_and_b32_e32 v1, 1, v8
	v_lshl_or_b32 v0, v1, 6, v0
	v_lshl_add_u32 v150, v9, 1, v0
	v_lshlrev_b32_e32 v0, 14, v4
	v_and_b32_e32 v0, 0xffff8000, v0
	s_waitcnt vmcnt(6)
	v_lshl_add_u32 v0, v5, 11, v0
	v_and_b32_e32 v1, 1, v4
	v_readlane_b32 s17, v253, 14
	v_writelane_b32 v255, s91, 18
	v_bitop3_b32 v17, v16, s5, v10 bitop3:0xde
	s_cmpk_lt_u32 s4, 0x100
	v_lshl_or_b32 v0, v1, 6, v0
	v_readlane_b32 s6, v254, 58
	v_readlane_b32 s18, v253, 15
	v_writelane_b32 v255, s94, 19
	s_cselect_b64 s[16:17], -1, 0
	s_mov_b32 s94, 0
	v_cmp_eq_u32_e64 s[4:5], 0, v11
	v_lshl_or_b32 v188, v11, 3, s8
	v_mov_b32_e32 v151, v161
	v_lshl_add_u32 v152, v6, 1, v0
	v_mov_b32_e32 v153, v161
	v_add_u32_e32 v189, 0, v17
	v_readlane_b32 s96, v254, 18
	s_mov_b32 s56, s6
	s_mov_b64 s[8:9], s[24:25]
	v_readlane_b32 s12, v253, 9
	v_readlane_b32 s13, v253, 10
	v_readlane_b32 s19, v253, 16
	v_readlane_b32 s22, v253, 19
	v_readlane_b32 s23, v253, 20
	s_barrier
	v_readlane_b32 s7, v254, 59
	s_branch .LBB0_596

.LBB0_715:
	s_lshl_b32 s86, s90, 15
	s_lshl_b64 s[6:7], s[86:87], 2
	v_readlane_b32 s5, v253, 48
	v_lshrrev_b32_e32 v16, 1, v10
	s_add_u32 s31, s5, s6
	v_readlane_b32 s5, v253, 49
	v_and_b32_e32 v16, 24, v16
	v_readlane_b32 s18, v254, 40
	s_addc_u32 s34, s5, s7
	v_and_b32_e32 v11, 15, v10
	v_lshlrev_b32_e32 v17, 1, v16
	v_lshlrev_b32_e32 v10, 2, v10
	s_lshl_b32 s3, s3, 5
	v_mov_b32_e32 v149, v161
	v_readlane_b32 s19, v254, 41
	v_lshl_or_b32 v156, s4, 6, v11
	v_lshl_or_b32 v11, v11, 6, v17
	s_lshl_b32 s4, s4, 13
	v_and_b32_e32 v10, 32, v10
	s_and_b32 s3, s3, 0x60
	s_add_i32 m0, s27, 0x18000
	v_lshl_add_u64 v[0:1], v[0:1], 0, s[38:39]
	v_lshl_add_u64 v[12:13], s[18:19], 0, v[148:149]
	v_mov_b32_e32 v147, v161
	v_bitop3_b32 v17, v11, s4, v10 bitop3:0xde
	s_lshl_b32 s4, s3, 7
	global_load_lds_dwordx4 v[0:1], off
	v_lshl_add_u64 v[0:1], v[2:3], 0, s[38:39]
	s_add_i32 m0, s27, 0x1a000
	s_add_i32 s35, s27, 0x8000
	s_add_i32 s84, s27, 0xa000
	v_lshl_add_u64 v[14:15], s[18:19], 0, v[146:147]
	v_bitop3_b32 v157, v11, s4, v10 bitop3:0xde
	global_load_lds_dwordx4 v[0:1], off
	v_lshl_add_u64 v[0:1], v[12:13], 0, s[38:39]
	s_mov_b32 m0, s35
	s_add_u32 s4, s20, 0x40080
	global_load_lds_dwordx4 v[0:1], off
	v_lshl_add_u64 v[0:1], v[14:15], 0, s[38:39]
	s_mov_b32 m0, s84
	s_addc_u32 s5, s21, 0
	global_load_lds_dwordx4 v[0:1], off
	s_add_i32 m0, s27, 0x1c000
	v_lshl_add_u64 v[0:1], s[4:5], 0, v[160:161]
	global_load_lds_dwordx4 v[0:1], off
	v_lshl_add_u64 v[0:1], s[4:5], 0, v[144:145]
	s_add_i32 m0, s27, 0x1e000
	s_cmpk_lt_u32 s2, 0x100
	global_load_lds_dwordx4 v[0:1], off
	s_waitcnt vmcnt(8)
	s_barrier
	v_lshlrev_b32_e32 v0, 14, v8
	v_and_b32_e32 v0, 0xffff8000, v0
	v_lshl_add_u32 v0, v7, 11, v0
	v_and_b32_e32 v1, 1, v8
	v_lshl_or_b32 v0, v1, 6, v0
	v_lshl_add_u32 v150, v9, 1, v0
	v_lshlrev_b32_e32 v0, 14, v4
	v_and_b32_e32 v0, 0xffff8000, v0
	s_waitcnt vmcnt(6)
	v_lshl_add_u32 v0, v5, 11, v0
	v_and_b32_e32 v1, 1, v4
	v_lshl_or_b32 v0, v1, 6, v0
	v_readlane_b32 s4, v254, 38
	s_cselect_b64 s[6:7], -1, 0
	v_or_b32_e32 v158, s3, v16
	v_mov_b32_e32 v151, v161
	v_lshl_add_u32 v152, v6, 1, v0
	v_mov_b32_e32 v153, v161
	s_mov_b32 s85, 0
	v_add_u32_e32 v159, 0, v17
	v_readlane_b32 s3, v254, 35
	s_mov_b32 s2, s4
	s_barrier
	v_readlane_b32 s5, v254, 39
	s_branch .LBB0_718

.LBB0_781:
	s_add_i32 s5, s90, 1
	s_add_u32 s65, s91, 0x5000
	s_addc_u32 s85, s94, 0
	s_lshl_b32 s86, s5, 10
	v_readlane_b32 s8, v253, 5
	s_lshl_b64 s[6:7], s[86:87], 2
	v_readlane_b32 s18, v253, 15
	v_readlane_b32 s9, v253, 6
	v_readlane_b32 s19, v253, 16
	s_add_u32 s8, s18, s6
	s_mul_i32 s86, s5, 0xc000
	s_addc_u32 s9, s19, s7
	s_lshl_b64 s[6:7], s[86:87], 2
	v_readlane_b32 s5, v253, 40
	s_add_u32 s5, s5, s6
	v_readlane_b32 s6, v253, 41
	s_addc_u32 s6, s6, s7
	s_add_u32 s86, s5, 0x1000
	v_readlane_b32 s10, v253, 7
	s_addc_u32 s88, s6, 0
	v_readlane_b32 s11, v253, 8
	s_add_u32 s10, s42, 0x40000
	v_readlane_b32 s26, v254, 60
	s_addc_u32 s11, s43, 0
	v_bfe_u32 v11, v10, 4, 2
	s_lshl_b32 s3, s3, 5
	v_mov_b32_e32 v149, v161
	v_readlane_b32 s27, v254, 61
	v_and_b32_e32 v16, 15, v10
	v_lshlrev_b32_e32 v17, 4, v11
	v_lshlrev_b32_e32 v10, 2, v10
	s_and_b32 s6, s3, 0x60
	s_add_i32 m0, s31, 0x18000
	v_lshl_add_u64 v[0:1], v[0:1], 0, s[38:39]
	v_lshl_add_u64 v[12:13], s[26:27], 0, v[148:149]
	v_mov_b32_e32 v147, v161
	v_lshl_or_b32 v184, s4, 6, v16
	v_lshl_or_b32 v16, v16, 6, v17
	s_lshl_b32 s4, s4, 13
	v_and_b32_e32 v10, 32, v10
	s_lshl_b32 s3, s6, 7
	global_load_lds_dwordx4 v[0:1], off
	v_lshl_add_u64 v[0:1], v[2:3], 0, s[38:39]
	s_add_i32 m0, s31, 0x1a000
	s_add_i32 s42, s31, 0x8000
	s_add_i32 s43, s31, 0xa000
	v_lshl_add_u64 v[14:15], s[26:27], 0, v[146:147]
	v_bitop3_b32 v17, v16, s4, v10 bitop3:0xde
	global_load_lds_dwordx4 v[0:1], off
	v_lshl_add_u64 v[0:1], v[12:13], 0, s[38:39]
	s_mov_b32 m0, s42
	s_add_u32 s4, s24, 0x100080
	global_load_lds_dwordx4 v[0:1], off
	v_lshl_add_u64 v[0:1], v[14:15], 0, s[38:39]
	s_mov_b32 m0, s43
	s_addc_u32 s5, s25, 0
	global_load_lds_dwordx4 v[0:1], off
	s_add_i32 m0, s31, 0x1c000
	v_lshl_add_u64 v[0:1], s[4:5], 0, v[160:161]
	global_load_lds_dwordx4 v[0:1], off
	v_lshl_add_u64 v[0:1], s[4:5], 0, v[144:145]
	s_add_i32 m0, s31, 0x1e000
	v_readlane_b32 s14, v253, 11
	global_load_lds_dwordx4 v[0:1], off
	s_waitcnt vmcnt(8)
	s_barrier
	v_lshlrev_b32_e32 v0, 16, v8
	v_and_b32_e32 v0, 0xfffe0000, v0
	v_lshl_add_u32 v0, v7, 13, v0
	v_and_b32_e32 v1, 1, v8
	v_lshl_or_b32 v0, v1, 6, v0
	v_readlane_b32 s15, v253, 12
	v_lshl_add_u32 v150, v9, 1, v0
	v_lshlrev_b32_e32 v0, 16, v4
	v_readlane_b32 s4, v254, 10
	v_readlane_b32 s14, v255, 6
	v_and_b32_e32 v0, 0xfffe0000, v0
	v_readlane_b32 s12, v253, 9
	v_readlane_b32 s13, v253, 10
	s_waitcnt vmcnt(6)
	s_cmpk_lt_u32 s2, 0x100
	v_readlane_b32 s5, v254, 11
	v_readlane_b32 s15, v255, 7
	v_lshl_add_u32 v0, v5, 13, v0
	v_and_b32_e32 v1, 1, v4
	s_cselect_b64 s[12:13], -1, 0
	s_nor_b64 s[14:15], s[14:15], s[4:5]
	v_lshl_or_b32 v0, v1, 6, v0
	v_readlane_b32 s4, v254, 58
	v_readlane_b32 s16, v253, 13
	v_bitop3_b32 v185, v16, s3, v10 bitop3:0xde
	s_mov_b32 s89, 0
	v_cmp_eq_u32_e64 s[2:3], 0, v11
	v_lshl_or_b32 v186, v11, 3, s6
	v_mov_b32_e32 v151, v161
	v_lshl_add_u32 v152, v6, 1, v0
	v_mov_b32_e32 v153, v161
	v_add_u32_e32 v187, 0, v17
	v_readlane_b32 s94, v254, 18
	s_mov_b32 s56, s4
	s_mov_b64 s[6:7], s[26:27]
	v_readlane_b32 s17, v253, 14
	v_readlane_b32 s20, v253, 17
	v_readlane_b32 s21, v253, 18
	v_readlane_b32 s22, v253, 19
	v_readlane_b32 s23, v253, 20
	s_barrier
	v_readlane_b32 s5, v254, 59
	s_branch .LBB0_784
